# k34_sleep10
# baseline (speedup 1.0000x reference)
; #define PH_SYNC(n) run_phase<n>(p, smem); grid.sync();
; __global__ void __launch_bounds__(256, 2) hybrid_fwd(Params p) {
;   __shared__ __attribute__((aligned(16))) char smem[SMEM_BYTES];
;   cg::grid_group grid = cg::this_grid();
;   PH_SYNC(0) PH_SYNC(1) PH_SYNC(2) PH_SYNC(3) PH_SYNC(4) PH_SYNC(5) PH_SYNC(6) PH_SYNC(7)
;   PH_SYNC(8) PH_SYNC(17) PH_SYNC(9) PH_SYNC(10) PH_SYNC(11) PH_SYNC(12) PH_SYNC(13) PH_SYNC(14) PH_SYNC(15)
;   PH_SYNC(16)
.Lmy_gs_poll_1:
	s_sleep 10
	global_load_dword v0, v2, s[10:11] sc1
	s_add_u32 s13, s13, 1
	s_waitcnt vmcnt(0)
	v_cmp_ge_u32_e32 vcc, v0, v1
	s_cmp_lg_u64 vcc, 0
	s_cbranch_scc1 .Lmy_gs_done_1
	s_cmp_lt_u32 s13, 0x40000
	s_cbranch_scc1 .Lmy_gs_poll_1

; #define PH_SYNC(n) run_phase<n>(p, smem); grid.sync();
; __global__ void __launch_bounds__(256, 2) hybrid_fwd(Params p) {
;   __shared__ __attribute__((aligned(16))) char smem[SMEM_BYTES];
;   cg::grid_group grid = cg::this_grid();
;   PH_SYNC(0) PH_SYNC(1) PH_SYNC(2) PH_SYNC(3) PH_SYNC(4) PH_SYNC(5) PH_SYNC(6) PH_SYNC(7)
;   PH_SYNC(8) PH_SYNC(17) PH_SYNC(9) PH_SYNC(10) PH_SYNC(11) PH_SYNC(12) PH_SYNC(13) PH_SYNC(14) PH_SYNC(15)
;   PH_SYNC(16)
.Lmy_gs_poll_3:
	s_sleep 10
	global_load_dword v0, v2, s[8:9] sc1
	s_add_u32 s11, s11, 1
	s_waitcnt vmcnt(0)
	v_cmp_ge_u32_e32 vcc, v0, v1
	s_cmp_lg_u64 vcc, 0
	s_cbranch_scc1 .Lmy_gs_done_3
	s_cmp_lt_u32 s11, 0x40000
	s_cbranch_scc1 .Lmy_gs_poll_3

; #define PH_SYNC(n) run_phase<n>(p, smem); grid.sync();
; __global__ void __launch_bounds__(256, 2) hybrid_fwd(Params p) {
;   __shared__ __attribute__((aligned(16))) char smem[SMEM_BYTES];
;   cg::grid_group grid = cg::this_grid();
;   PH_SYNC(0) PH_SYNC(1) PH_SYNC(2) PH_SYNC(3) PH_SYNC(4) PH_SYNC(5) PH_SYNC(6) PH_SYNC(7)
;   PH_SYNC(8) PH_SYNC(17) PH_SYNC(9) PH_SYNC(10) PH_SYNC(11) PH_SYNC(12) PH_SYNC(13) PH_SYNC(14) PH_SYNC(15)
;   PH_SYNC(16)
.Lmy_gs_poll_5:
	s_sleep 10
	global_load_dword v0, v2, s[12:13] sc1
	s_add_u32 s15, s15, 1
	s_waitcnt vmcnt(0)
	v_cmp_ge_u32_e32 vcc, v0, v1
	s_cmp_lg_u64 vcc, 0
	s_cbranch_scc1 .Lmy_gs_done_5
	s_cmp_lt_u32 s15, 0x40000
	s_cbranch_scc1 .Lmy_gs_poll_5

; #define PH_SYNC(n) run_phase<n>(p, smem); grid.sync();
; __global__ void __launch_bounds__(256, 2) hybrid_fwd(Params p) {
;   __shared__ __attribute__((aligned(16))) char smem[SMEM_BYTES];
;   cg::grid_group grid = cg::this_grid();
;   PH_SYNC(0) PH_SYNC(1) PH_SYNC(2) PH_SYNC(3) PH_SYNC(4) PH_SYNC(5) PH_SYNC(6) PH_SYNC(7)
;   PH_SYNC(8) PH_SYNC(17) PH_SYNC(9) PH_SYNC(10) PH_SYNC(11) PH_SYNC(12) PH_SYNC(13) PH_SYNC(14) PH_SYNC(15)
;   PH_SYNC(16)
.Lsy0_poll:
	s_sleep 10
	global_load_dword v0, v2, s[26:27] sc1
	s_add_u32 s25, s25, 1
	s_waitcnt vmcnt(0)
	v_cmp_ge_u32_e32 vcc, v0, v1
	s_cmp_lg_u64 vcc, 0
	s_cbranch_scc1 .Lsy0_done
	s_cmp_lt_u32 s25, 0x40000
	s_cbranch_scc1 .Lsy0_poll

; #define PH_SYNC(n) run_phase<n>(p, smem); grid.sync();
; __global__ void __launch_bounds__(256, 2) hybrid_fwd(Params p) {
;   __shared__ __attribute__((aligned(16))) char smem[SMEM_BYTES];
;   cg::grid_group grid = cg::this_grid();
;   PH_SYNC(0) PH_SYNC(1) PH_SYNC(2) PH_SYNC(3) PH_SYNC(4) PH_SYNC(5) PH_SYNC(6) PH_SYNC(7)
;   PH_SYNC(8) PH_SYNC(17) PH_SYNC(9) PH_SYNC(10) PH_SYNC(11) PH_SYNC(12) PH_SYNC(13) PH_SYNC(14) PH_SYNC(15)
;   PH_SYNC(16)
.Lmy_gs_poll_9:
	s_sleep 10
	global_load_dword v0, v2, s[14:15] sc1
	s_add_u32 s17, s17, 1
	s_waitcnt vmcnt(0)
	v_cmp_ge_u32_e32 vcc, v0, v1
	s_cmp_lg_u64 vcc, 0
	s_cbranch_scc1 .Lmy_gs_done_9
	s_cmp_lt_u32 s17, 0x40000
	s_cbranch_scc1 .Lmy_gs_poll_9

; #define PH_SYNC(n) run_phase<n>(p, smem); grid.sync();
; __global__ void __launch_bounds__(256, 2) hybrid_fwd(Params p) {
;   __shared__ __attribute__((aligned(16))) char smem[SMEM_BYTES];
;   cg::grid_group grid = cg::this_grid();
;   PH_SYNC(0) PH_SYNC(1) PH_SYNC(2) PH_SYNC(3) PH_SYNC(4) PH_SYNC(5) PH_SYNC(6) PH_SYNC(7)
;   PH_SYNC(8) PH_SYNC(17) PH_SYNC(9) PH_SYNC(10) PH_SYNC(11) PH_SYNC(12) PH_SYNC(13) PH_SYNC(14) PH_SYNC(15)
;   PH_SYNC(16)
.Lmy_gs_poll_16:
	s_sleep 10
	global_load_dword v0, v2, s[6:7] sc1
	s_add_u32 s9, s9, 1
	s_waitcnt vmcnt(0)
	v_cmp_ge_u32_e32 vcc, v0, v1
	s_cmp_lg_u64 vcc, 0
	s_cbranch_scc1 .Lmy_gs_done_16
	s_cmp_lt_u32 s9, 0x40000
	s_cbranch_scc1 .Lmy_gs_poll_16

; #define PH_SYNC(n) run_phase<n>(p, smem); grid.sync();
; __global__ void __launch_bounds__(256, 2) hybrid_fwd(Params p) {
;   __shared__ __attribute__((aligned(16))) char smem[SMEM_BYTES];
;   cg::grid_group grid = cg::this_grid();
;   PH_SYNC(0) PH_SYNC(1) PH_SYNC(2) PH_SYNC(3) PH_SYNC(4) PH_SYNC(5) PH_SYNC(6) PH_SYNC(7)
;   PH_SYNC(8) PH_SYNC(17) PH_SYNC(9) PH_SYNC(10) PH_SYNC(11) PH_SYNC(12) PH_SYNC(13) PH_SYNC(14) PH_SYNC(15)
;   PH_SYNC(16)
.Lmy_gs_poll_17:
	s_sleep 10
	global_load_dword v0, v2, s[0:1] sc1
	s_add_u32 s5, s5, 1
	s_waitcnt vmcnt(0)
	v_cmp_ge_u32_e32 vcc, v0, v1
	s_cmp_lg_u64 vcc, 0
	s_cbranch_scc1 .Lmy_gs_done_17
	s_cmp_lt_u32 s5, 0x40000
	s_cbranch_scc1 .Lmy_gs_poll_17
